# next-layer weight conversion moved into idle tails of layer 0 (IN, GU2, DN2 phases): idle blocks convert the weight tiles whose buffers are already dead; the s=14 prep only does the remaining 256 tile
# speedup vs baseline: 1.0063x; 1.0029x over previous
; #define LAS __attribute__((address_space(3)))
; DI unsigned xb_add(unsigned* p, unsigned v) { return __hip_atomic_fetch_add(p, v, __ATOMIC_RELAXED, __HIP_MEMORY_SCOPE_AGENT); }
; DI unsigned xb_xcc_id() { return (unsigned)__builtin_amdgcn_s_getreg((3 << 11) | 20) & 0xFu; }
; DI XcdBarrier xcd_barrier_post(unsigned* bar, volatile LAS unsigned* st) {
;     XcdBarrier b; b.bar = bar; b.x = xb_xcc_id(); b.st = st;
;     if (threadIdx.x == 0) (void)xb_add(&bar[XB_XCNT(b.x)], 1u);
;     return b;
; extern "C" __global__ void __launch_bounds__(512, 2) fwd_kernel(Params p, int ph0, int ph1) {
;     extern __shared__ __attribute__((aligned(16))) char smem[];
;     ...
;     __shared__ uint4 xb_words;
;     if (threadIdx.x == 0) xb_words = make_uint4(0u, 0u, 0u, 0u);
;     __syncthreads();
;     XcdBarrier xb = xcd_barrier_post((unsigned*)(p.ws + B_BAR), (volatile LAS unsigned*)&xb_words);
fwd_kernel:
	v_mov_b32_e32 v241, 0x82000
	v_and_b32_e32 v193, 0x3ff, v0
	v_writelane_b32 v240, s2, 0
	s_load_dwordx2 s[2:3], s[0:1], 0x110
	s_load_dwordx4 s[4:7], s[0:1], 0x100
	s_waitcnt lgkmcnt(0)
	v_writelane_b32 v240, s2, 1
	s_nop 1
	v_writelane_b32 v240, s3, 2
	v_writelane_b32 v240, s4, 3
	s_nop 1
	v_writelane_b32 v240, s5, 4
	v_writelane_b32 v240, s6, 5
	v_writelane_b32 v240, s7, 6
	v_cmp_eq_u32_e64 s[4:5], 0, v193
	s_mov_b64 s[2:3], exec
	s_nop 0
	v_writelane_b32 v240, s4, 7
	s_nop 1
	v_writelane_b32 v240, s5, 8
	s_and_b64 s[4:5], s[2:3], s[4:5]
	s_mov_b64 exec, s[4:5]
	v_mov_b32_e32 v2, 0
	v_mov_b32_e32 v3, v2
	v_mov_b32_e32 v4, v2
	v_mov_b32_e32 v5, v2
	ds_write_b128 v2, v[2:5]
	s_or_b64 exec, exec, s[2:3]
	s_load_dwordx2 s[2:3], s[0:1], 0x110
	s_waitcnt lgkmcnt(0)
	s_barrier
	s_getreg_b32 s4, hwreg(HW_REG_XCC_ID, 0, 4)
	s_add_u32 s2, s2, 0x13095000
	s_addc_u32 s3, s3, 0
	s_and_b32 s20, s4, 15
	s_mov_b64 s[4:5], exec
	v_readlane_b32 s6, v240, 7
	v_readlane_b32 s7, v240, 8
	s_and_b64 s[6:7], s[4:5], s[6:7]
	s_mov_b64 exec, s[6:7]
	s_cbranch_execz .LBB0_5
	s_mov_b64 s[6:7], exec
	v_mbcnt_lo_u32_b32 v1, s6, 0
	v_mbcnt_hi_u32_b32 v1, s7, v1
	v_cmp_eq_u32_e32 vcc, 0, v1
	s_and_b64 s[8:9], exec, vcc
	s_mov_b64 exec, s[8:9]
	s_cbranch_execz .LBB0_5
	s_lshl_b32 s8, s20, 8
	s_bcnt1_i32_b64 s6, s[6:7]
	v_mov_b32_e32 v1, s8
	v_mov_b32_e32 v2, s6
	global_atomic_add v1, v2, s[2:3] offset:1024

; DI void prep_phase(const Params& p, int l, int bid, int nb, char* smem, const int tid) {
;     ...
;     for (int t = bid; t < 1348; t += nb) {
;         const float* src; bf16_t* dst; int K, N, mode, base;
;         if (t < 352) { src = p.in[13] + (size_t)l * 1024 * 5632; dst = (bf16_t*)(p.ws + W_GU1); K = 1024; N = 5632; mode = 1; base = 0; }
;         else if (t < 528) { src = p.in[14] + (size_t)l * 2816 * 1024; dst = (bf16_t*)(p.ws + W_DN1); K = 2816; N = 1024; mode = 0; base = 352; }
;         else if (t < 656) { src = p.in[17] + (size_t)l * 1024 * 1956; dst = (bf16_t*)(p.ws + W_IN); K = 1024; N = 1956; mode = 2; base = 528; }
;         else if (t < 668) { src = p.in[21] + (size_t)l * 256 * 768; dst = (bf16_t*)(p.ws + W_UQ); K = 256; N = 768; mode = 0; base = 656; }
;         else if (t < 676) { src = p.in[22] + (size_t)l * 128 * 1024; dst = (bf16_t*)(p.ws + W_UKV); K = 128; N = 1024; mode = 0; base = 668; }
;         else if (t < 740) { src = p.in[24] + (size_t)l * 1024 * 1024; dst = (bf16_t*)(p.ws + W_OUT); K = 1024; N = 1024; mode = 0; base = 676; }
;         else if (t < 1092) { src = p.in[27] + (size_t)l * 1024 * 5632; dst = (bf16_t*)(p.ws + W_GU2); K = 1024; N = 5632; mode = 1; base = 740; }
;         else if (t < 1268) { src = p.in[28] + (size_t)l * 2816 * 1024; dst = (bf16_t*)(p.ws + W_DN2); K = 2816; N = 1024; mode = 0; base = 1092; }
;         else if (t < 1332) { src = p.in[30] + (size_t)l * 1024 * 1024; dst = (bf16_t*)(p.ws + W_PG); K = 1024; N = 1024; mode = 0; base = 1268; }
;         else { src = p.in[31] + (size_t)l * 256 * 1024; dst = (bf16_t*)(p.ws + W_PP); K = 256; N = 1024; mode = 0; base = 1332; }
;         const int lt = t - base, nkt = K / 64;
;         wtile(src, dst, K, N, mode, lt % nkt, lt / nkt, tile, tid);
.Lprep_early:
	v_readlane_b32 s0, v231, 0
	s_mov_b64 s[64:65], s[46:47]
	s_cmpk_gt_i32 s0, 0x543
	v_readlane_b32 s1, v231, 1
	s_cbranch_scc1 .LBB0_101
	v_lshlrev_b32_e32 v0, 2, v227
	v_and_b32_e32 v17, 0xfc, v0
	v_ashrrev_i32_e32 v0, 3, v227
	v_ashrrev_i32_e32 v3, 5, v227
	v_and_b32_e32 v42, -8, v0
	s_movk_i32 s0, 0x410
	v_or_b32_e32 v0, 7, v0
	v_and_b32_e32 v18, -8, v3
	v_mul_lo_u32 v2, v42, s0
	v_mul_lo_u32 v0, v0, s0
	v_mul_lo_u32 v4, v18, s0
	s_add_u32 s0, s88, 0x2220000
	s_addc_u32 s1, s89, 0
	s_add_u32 s36, s88, 0x1720000
	s_addc_u32 s37, s89, 0
	s_add_u32 s38, s88, 0x1520000
	s_addc_u32 s39, s89, 0
	s_add_u32 s40, s88, 0x14e0000
	s_addc_u32 s41, s89, 0
	s_add_u32 s44, s88, 0x1480000
	s_addc_u32 s45, s89, 0
	s_add_u32 s46, s88, 0x1080000
	v_and_b32_e32 v43, 0xff, v227
	s_addc_u32 s47, s89, 0
	v_lshl_add_u32 v1, v17, 2, 16
	v_and_b32_e32 v44, 15, v227
	v_lshl_add_u32 v3, v43, 2, 16
	s_add_u32 s48, s88, 0xb00000
	v_ashrrev_i32_e32 v19, 31, v18
	s_addc_u32 s49, s89, 0
	v_or_b32_e32 v45, 16, v44
	v_add_u32_e32 v46, v1, v2
	v_add_u32_e32 v47, v1, v0
	v_add_u32_e32 v48, v3, v4
	v_readlane_b32 s2, v231, 0
	v_readlane_b32 s3, v238, 54
	s_cmpk_eq_i32 s3, 0x100
	s_cselect_b32 s3, 0x444, 0
	s_add_i32 s2, s2, s3
	v_readlane_b32 s3, v231, 1
	s_branch .LBB0_44

; DI unsigned pk2(float lo, float hi) { const f32x2 v = {lo, hi}; return __builtin_bit_cast(unsigned, __builtin_convertvector(v, bf2_t)); }
; DI void prep_phase(const Params& p, int l, int bid, int nb, char* smem, const int tid) {
;     ...
;     {
;         bf16_t* pbf = (bf16_t*)(p.ws + W_PBF);
;         const int total = MT * 256 / 8;
;         for (int i = bid * NTHR + tid; i < total; i += nb * NTHR) {
;             const size_t e = (size_t)i * 8;
;             const float* s = (e < (size_t)NP * 256) ? (p.in[2] + (size_t)l * NP * 256 + e) : (p.in[3] + (size_t)l * NS * 256 + (e - (size_t)NP * 256));
;             const float4 a = *(const float4*)s, b = *(const float4*)(s + 4);
;             u32x4 w; w.x = pk2(a.x, a.y); w.y = pk2(a.z, a.w); w.z = pk2(b.x, b.y); w.w = pk2(b.z, b.w);
;             *(u32x4*)(pbf + e) = w;
;         }
.LBB0_104:
	s_or_b64 exec, exec, s[0:1]
	v_readlane_b32 s0, v241, 3
	v_cmp_gt_i32_e32 vcc, s0, v0
	s_and_saveexec_b64 s[0:1], vcc
	v_readlane_b32 s10, v238, 62
	v_readlane_b32 s38, v238, 44
	v_readlane_b32 s40, v238, 46
	v_readlane_b32 s44, v238, 50
	v_readlane_b32 s48, v238, 52
	s_mov_b64 s[46:47], s[64:65]
	v_readlane_b32 s11, v238, 63
	v_readlane_b32 s39, v238, 45
	v_readlane_b32 s41, v238, 47
	v_readlane_b32 s45, v238, 51
	v_readlane_b32 s49, v238, 53
	s_mov_b32 s33, 0x81fff
	s_mov_b64 s[50:51], 0x400000
	s_cbranch_execz .LBB0_107
	v_lshl_add_u64 v[4:5], v[0:1], 4, s[88:89]
	s_mov_b64 s[2:3], 0x2a20000
	v_lshlrev_b64 v[2:3], 5, v[0:1]
	v_lshl_add_u64 v[4:5], v[4:5], 0, s[2:3]
	v_lshlrev_b64 v[6:7], 3, v[0:1]
	s_mov_b64 s[36:37], 0

; DI unsigned pk2(float lo, float hi) { const f32x2 v = {lo, hi}; return __builtin_bit_cast(unsigned, __builtin_convertvector(v, bf2_t)); }
; DI void prep_phase(const Params& p, int l, int bid, int nb, char* smem, const int tid) {
;     ...
;     {
;         bf16_t* pbf = (bf16_t*)(p.ws + W_PBF);
;         const int total = MT * 256 / 8;
;         for (int i = bid * NTHR + tid; i < total; i += nb * NTHR) {
;             const size_t e = (size_t)i * 8;
;             const float* s = (e < (size_t)NP * 256) ? (p.in[2] + (size_t)l * NP * 256 + e) : (p.in[3] + (size_t)l * NS * 256 + (e - (size_t)NP * 256));
;             const float4 a = *(const float4*)s, b = *(const float4*)(s + 4);
;             u32x4 w; w.x = pk2(a.x, a.y); w.y = pk2(a.z, a.w); w.z = pk2(b.x, b.y); w.w = pk2(b.z, b.w);
;             *(u32x4*)(pbf + e) = w;
;         }
;     }
; }
.LBB0_108:
	v_readlane_b32 s0, v238, 54
	s_cmpk_eq_i32 s0, 0x4000
	s_cbranch_scc1 .Lprep_drv

; DI void prep_phase(const Params& p, int l, int bid, int nb, char* smem, const int tid) {
;     ...
;     for (int t = bid; t < 1348; t += nb) {
;         const float* src; bf16_t* dst; int K, N, mode, base;
;         if (t < 352) { src = p.in[13] + (size_t)l * 1024 * 5632; dst = (bf16_t*)(p.ws + W_GU1); K = 1024; N = 5632; mode = 1; base = 0; }
;         else if (t < 528) { src = p.in[14] + (size_t)l * 2816 * 1024; dst = (bf16_t*)(p.ws + W_DN1); K = 2816; N = 1024; mode = 0; base = 352; }
;         else if (t < 656) { src = p.in[17] + (size_t)l * 1024 * 1956; dst = (bf16_t*)(p.ws + W_IN); K = 1024; N = 1956; mode = 2; base = 528; }
;         else if (t < 668) { src = p.in[21] + (size_t)l * 256 * 768; dst = (bf16_t*)(p.ws + W_UQ); K = 256; N = 768; mode = 0; base = 656; }
;         else if (t < 676) { src = p.in[22] + (size_t)l * 128 * 1024; dst = (bf16_t*)(p.ws + W_UKV); K = 128; N = 1024; mode = 0; base = 668; }
;         else if (t < 740) { src = p.in[24] + (size_t)l * 1024 * 1024; dst = (bf16_t*)(p.ws + W_OUT); K = 1024; N = 1024; mode = 0; base = 676; }
;         else if (t < 1092) { src = p.in[27] + (size_t)l * 1024 * 5632; dst = (bf16_t*)(p.ws + W_GU2); K = 1024; N = 5632; mode = 1; base = 740; }
;         else if (t < 1268) { src = p.in[28] + (size_t)l * 2816 * 1024; dst = (bf16_t*)(p.ws + W_DN2); K = 2816; N = 1024; mode = 0; base = 1092; }
;         else if (t < 1332) { src = p.in[30] + (size_t)l * 1024 * 1024; dst = (bf16_t*)(p.ws + W_PG); K = 1024; N = 1024; mode = 0; base = 1268; }
;         else { src = p.in[31] + (size_t)l * 256 * 1024; dst = (bf16_t*)(p.ws + W_PP); K = 256; N = 1024; mode = 0; base = 1332; }
;         const int lt = t - base, nkt = K / 64;
;         wtile(src, dst, K, N, mode, lt % nkt, lt / nkt, tile, tid);
;     }
.Lprep_drv:
	v_readlane_b32 s0, v241, 0
	v_readlane_b32 s1, v241, 1
	v_readlane_b32 s2, v241, 2
	s_cmp_ge_u32 s0, s2
	s_cbranch_scc1 .Lprep_fin
	s_add_u32 s1, s0, s1
	s_nop 3
	v_writelane_b32 v231, s0, 0
	v_writelane_b32 v241, s1, 0
	s_branch .Lprep_early
.Lprep_fin:
	v_readlane_b32 s0, v240, 0
	s_movk_i32 s1, 0x100
	s_mov_b32 s2, 0x82000
	s_nop 3
	v_writelane_b32 v231, s0, 0
	v_writelane_b32 v238, s1, 54
	v_writelane_b32 v241, s2, 3
	s_branch .Lprep_norm

; DI void prep_phase(const Params& p, int l, int bid, int nb, char* smem, const int tid) {
;     ...
;     for (int t = bid; t < 1348; t += nb) {
;         const float* src; bf16_t* dst; int K, N, mode, base;
;         if (t < 352) { src = p.in[13] + (size_t)l * 1024 * 5632; dst = (bf16_t*)(p.ws + W_GU1); K = 1024; N = 5632; mode = 1; base = 0; }
;         else if (t < 528) { src = p.in[14] + (size_t)l * 2816 * 1024; dst = (bf16_t*)(p.ws + W_DN1); K = 2816; N = 1024; mode = 0; base = 352; }
;         else if (t < 656) { src = p.in[17] + (size_t)l * 1024 * 1956; dst = (bf16_t*)(p.ws + W_IN); K = 1024; N = 1956; mode = 2; base = 528; }
;         else if (t < 668) { src = p.in[21] + (size_t)l * 256 * 768; dst = (bf16_t*)(p.ws + W_UQ); K = 256; N = 768; mode = 0; base = 656; }
;         else if (t < 676) { src = p.in[22] + (size_t)l * 128 * 1024; dst = (bf16_t*)(p.ws + W_UKV); K = 128; N = 1024; mode = 0; base = 668; }
;         else if (t < 740) { src = p.in[24] + (size_t)l * 1024 * 1024; dst = (bf16_t*)(p.ws + W_OUT); K = 1024; N = 1024; mode = 0; base = 676; }
;         else if (t < 1092) { src = p.in[27] + (size_t)l * 1024 * 5632; dst = (bf16_t*)(p.ws + W_GU2); K = 1024; N = 5632; mode = 1; base = 740; }
;         else if (t < 1268) { src = p.in[28] + (size_t)l * 2816 * 1024; dst = (bf16_t*)(p.ws + W_DN2); K = 2816; N = 1024; mode = 0; base = 1092; }
;         else if (t < 1332) { src = p.in[30] + (size_t)l * 1024 * 1024; dst = (bf16_t*)(p.ws + W_PG); K = 1024; N = 1024; mode = 0; base = 1268; }
;         else { src = p.in[31] + (size_t)l * 256 * 1024; dst = (bf16_t*)(p.ws + W_PP); K = 256; N = 1024; mode = 0; base = 1332; }
;         const int lt = t - base, nkt = K / 64;
;         wtile(src, dst, K, N, mode, lt % nkt, lt / nkt, tile, tid);
;     }
;     DI void init(int ntm_, int ntn_, int bid, int nb) {
;         ntm = ntm_; ntn = ntn_;
;         const int nt = ntm * ntn;
;         if ((nb & 7) == 0) { const int x = bid & 7, per = (nt + 7) >> 3; L = x * per + (bid >> 3); end = min((x + 1) * per, nt); step = nb >> 3; }
;         else { L = bid; end = nt; step = nb; }
.Lgu_exit:
	v_readlane_b32 s1, v231, 4
	v_readlane_b32 s2, v238, 54
	v_readlane_b32 s3, v240, 0
	s_cmp_lg_u32 s1, 0
	s_cbranch_scc1 .LBB0_860
	s_cmpk_lg_i32 s2, 0x100
	s_cbranch_scc1 .LBB0_860
	s_cmp_eq_u32 s61, 0
	s_cbranch_scc1 .LBB0_860
	s_and_b32 s1, s3, 7
	s_lshr_b32 s2, s3, 3
	s_cmp_eq_u32 s1, 7
	s_cselect_b32 s3, 17, 19
	s_cmp_lt_u32 s2, s3
	s_cbranch_scc1 .LBB0_860
	s_sub_u32 s2, s2, s3
	s_mul_i32 s1, s1, 13
	s_add_u32 s1, s1, s2
	s_add_u32 s1, s1, 0x210
	s_movk_i32 s2, 0x6a
	s_movk_i32 s3, 0x2e4
	s_waitcnt vmcnt(0) lgkmcnt(0)
	s_mov_b32 s0, 0
	s_nop 3
	v_writelane_b32 v241, s1, 0
	v_writelane_b32 v241, s2, 1
	v_writelane_b32 v241, s3, 2
	v_writelane_b32 v241, s0, 3
	s_movk_i32 s2, 0x4000
	s_nop 3
	v_writelane_b32 v238, s2, 54
	v_mov_b32_e32 v227, v193
	s_branch .Lprep_drv
.Lgyd_exit:
	v_readlane_b32 s1, v231, 4
	v_readlane_b32 s2, v238, 54
	v_readlane_b32 s3, v240, 0
	s_cmp_lg_u32 s1, 0
	s_cbranch_scc1 .LBB0_860
	s_cmpk_lg_i32 s2, 0x100
	s_cbranch_scc1 .LBB0_860
	s_cmp_lg_u32 s61, 0x2220000
	s_cbranch_scc1 .LBB0_860
	s_cmp_lt_u32 s3, 44
	s_cbranch_scc1 .LBB0_860
	s_add_u32 s1, s3, 0x2b8
	s_movk_i32 s2, 0xd4
	s_movk_i32 s3, 0x444
	s_waitcnt vmcnt(0) lgkmcnt(0)
	s_mov_b32 s0, 0
	s_nop 3
	v_writelane_b32 v241, s1, 0
	v_writelane_b32 v241, s2, 1
	v_writelane_b32 v241, s3, 2
	v_writelane_b32 v241, s0, 3
	s_movk_i32 s2, 0x4000
	s_nop 3
	v_writelane_b32 v238, s2, 54
	v_mov_b32_e32 v227, v193
	s_branch .Lprep_drv

; DI void prep_phase(const Params& p, int l, int bid, int nb, char* smem, const int tid) {
;     ...
;     for (int t = bid; t < 1348; t += nb) {
;         const float* src; bf16_t* dst; int K, N, mode, base;
;         if (t < 352) { src = p.in[13] + (size_t)l * 1024 * 5632; dst = (bf16_t*)(p.ws + W_GU1); K = 1024; N = 5632; mode = 1; base = 0; }
;         else if (t < 528) { src = p.in[14] + (size_t)l * 2816 * 1024; dst = (bf16_t*)(p.ws + W_DN1); K = 2816; N = 1024; mode = 0; base = 352; }
;         else if (t < 656) { src = p.in[17] + (size_t)l * 1024 * 1956; dst = (bf16_t*)(p.ws + W_IN); K = 1024; N = 1956; mode = 2; base = 528; }
;         else if (t < 668) { src = p.in[21] + (size_t)l * 256 * 768; dst = (bf16_t*)(p.ws + W_UQ); K = 256; N = 768; mode = 0; base = 656; }
;         else if (t < 676) { src = p.in[22] + (size_t)l * 128 * 1024; dst = (bf16_t*)(p.ws + W_UKV); K = 128; N = 1024; mode = 0; base = 668; }
;         else if (t < 740) { src = p.in[24] + (size_t)l * 1024 * 1024; dst = (bf16_t*)(p.ws + W_OUT); K = 1024; N = 1024; mode = 0; base = 676; }
;         else if (t < 1092) { src = p.in[27] + (size_t)l * 1024 * 5632; dst = (bf16_t*)(p.ws + W_GU2); K = 1024; N = 5632; mode = 1; base = 740; }
;         else if (t < 1268) { src = p.in[28] + (size_t)l * 2816 * 1024; dst = (bf16_t*)(p.ws + W_DN2); K = 2816; N = 1024; mode = 0; base = 1092; }
;         else if (t < 1332) { src = p.in[30] + (size_t)l * 1024 * 1024; dst = (bf16_t*)(p.ws + W_PG); K = 1024; N = 1024; mode = 0; base = 1268; }
;         else { src = p.in[31] + (size_t)l * 256 * 1024; dst = (bf16_t*)(p.ws + W_PP); K = 256; N = 1024; mode = 0; base = 1332; }
;         const int lt = t - base, nkt = K / 64;
;         wtile(src, dst, K, N, mode, lt % nkt, lt / nkt, tile, tid);
;     }
; DI void gemm_in(const Params& p, int l, int bid, int nb, char* smem, const int tid) {
;     ...
;     TileIter ti; ti.init(65, ntn, bid, nb);
;     int tm, tn, tm2 = 0, tn2 = 0;
;     bool have = ti.next(tm, tn);
;     Ring rg; rg.st = 0; rg.primed = 0;
;     for (; have; tm = tm2, tn = tn2) {
.Lin_stub:
	s_waitcnt vmcnt(0) lgkmcnt(0)
	s_barrier
	v_mov_b32_e32 v227, v193
	v_readlane_b32 s1, v231, 4
	v_readlane_b32 s2, v238, 54
	v_readlane_b32 s3, v240, 0
	s_cmp_lg_u32 s1, 0
	s_cbranch_scc1 .Lin_noprep
	s_cmpk_lg_i32 s2, 0x100
	s_cbranch_scc1 .Lin_noprep
	s_cmp_lt_u32 s3, 16
	s_cbranch_scc1 .Lin_noprep
	s_sub_u32 s1, s3, 16
	s_movk_i32 s2, 0xf0
	s_movk_i32 s3, 0x210
	s_waitcnt vmcnt(0) lgkmcnt(0)
	s_mov_b32 s0, 0
	s_nop 3
	v_writelane_b32 v241, s1, 0
	v_writelane_b32 v241, s2, 1
	v_writelane_b32 v241, s3, 2
	v_writelane_b32 v241, s0, 3
	s_movk_i32 s2, 0x4000
	s_nop 3
	v_writelane_b32 v238, s2, 54
	v_mov_b32_e32 v227, v193
	s_branch .Lprep_drv
.Lin_noprep:
	v_readlane_b32 s3, v231, 0
	v_readlane_b32 s0, v238, 54
	s_add_i32 s3, s3, 0x400
	v_readfirstlane_b32 s33, v227
	s_movk_i32 s2, 0x410
	s_mov_b32 s10, s0
	s_branch .Lin_old661

; extern "C" __global__ void __launch_bounds__(512, 2) fwd_kernel(Params p, int ph0, int ph1) {
;     extern __shared__ __attribute__((aligned(16))) char smem[];
	.amdhsa_kernel fwd_kernel
		.amdhsa_group_segment_fixed_size 16
		.amdhsa_private_segment_fixed_size 0
		.amdhsa_kernarg_size 544
		.amdhsa_user_sgpr_count 2
		.amdhsa_user_sgpr_dispatch_ptr 0
		.amdhsa_user_sgpr_queue_ptr 0
		.amdhsa_user_sgpr_kernarg_segment_ptr 1
		.amdhsa_user_sgpr_dispatch_id 0
		.amdhsa_user_sgpr_kernarg_preload_length 0
		.amdhsa_user_sgpr_kernarg_preload_offset 0
		.amdhsa_user_sgpr_private_segment_size 0
		.amdhsa_uses_dynamic_stack 0
		.amdhsa_enable_private_segment 0
		.amdhsa_system_sgpr_workgroup_id_x 1
		.amdhsa_system_sgpr_workgroup_id_y 0
		.amdhsa_system_sgpr_workgroup_id_z 0
		.amdhsa_system_sgpr_workgroup_info 0
		.amdhsa_system_vgpr_workitem_id 2
		.amdhsa_next_free_vgpr 242
		.amdhsa_next_free_sgpr 100
		.amdhsa_accum_offset 244
		.amdhsa_reserve_vcc 1
		.amdhsa_float_round_mode_32 0
		.amdhsa_float_round_mode_16_64 0
		.amdhsa_float_denorm_mode_32 3
		.amdhsa_float_denorm_mode_16_64 3
		.amdhsa_dx10_clamp 1
		.amdhsa_ieee_mode 1
		.amdhsa_fp16_overflow 0
		.amdhsa_tg_split 0
		.amdhsa_exception_fp_ieee_invalid_op 0
		.amdhsa_exception_fp_denorm_src 0
		.amdhsa_exception_fp_ieee_div_zero 0
		.amdhsa_exception_fp_ieee_overflow 0
		.amdhsa_exception_fp_ieee_underflow 0
		.amdhsa_exception_fp_ieee_inexact 0
		.amdhsa_exception_int_div_zero 0
	.end_amdhsa_kernel

; extern "C" __global__ void __launch_bounds__(512, 2) fwd_kernel(Params p, int ph0, int ph1) {
;     extern __shared__ __attribute__((aligned(16))) char smem[];
amdhsa.kernels:
  - .agpr_count:     0
    .args:
      - .offset:         0
        .size:           280
        .value_kind:     by_value
      - .offset:         280
        .size:           4
        .value_kind:     by_value
      - .offset:         284
        .size:           4
        .value_kind:     by_value
      - .offset:         288
        .size:           4
        .value_kind:     hidden_block_count_x
      - .offset:         292
        .size:           4
        .value_kind:     hidden_block_count_y
      - .offset:         296
        .size:           4
        .value_kind:     hidden_block_count_z
      - .offset:         300
        .size:           2
        .value_kind:     hidden_group_size_x
      - .offset:         302
        .size:           2
        .value_kind:     hidden_group_size_y
      - .offset:         304
        .size:           2
        .value_kind:     hidden_group_size_z
      - .offset:         306
        .size:           2
        .value_kind:     hidden_remainder_x
      - .offset:         308
        .size:           2
        .value_kind:     hidden_remainder_y
      - .offset:         310
        .size:           2
        .value_kind:     hidden_remainder_z
      - .offset:         328
        .size:           8
        .value_kind:     hidden_global_offset_x
      - .offset:         336
        .size:           8
        .value_kind:     hidden_global_offset_y
      - .offset:         344
        .size:           8
        .value_kind:     hidden_global_offset_z
      - .offset:         352
        .size:           2
        .value_kind:     hidden_grid_dims
      - .offset:         376
        .size:           8
        .value_kind:     hidden_multigrid_sync_arg
      - .offset:         408
        .size:           4
        .value_kind:     hidden_dynamic_lds_size
    .group_segment_fixed_size: 16
    .kernarg_segment_align: 8
    .kernarg_segment_size: 544
    .language:       OpenCL C
    .language_version:
      - 2
      - 0
    .max_flat_workgroup_size: 512
    .name:           fwd_kernel
    .private_segment_fixed_size: 0
    .sgpr_count:     106
    .sgpr_spill_count: 263
    .symbol:         fwd_kernel.kd
    .uniform_work_group_size: 1
    .uses_dynamic_stack: false
    .vgpr_count:     242
    .vgpr_spill_count: 0
    .wavefront_size: 64
